# tail-row norm phases (4): loop-invariant gain vectors loaded once up front (in-chain loads become v_mov, per-load drains removed); layer-1 small-column wsm fill with 6 wide loads per thread
# speedup vs baseline: 1.0149x; 1.0149x over previous
.LBB0_1221:
	s_cmp_lt_i32 s88, 7
	s_cselect_b64 s[0:1], -1, 0
	s_cmp_gt_i32 s89, 6
	s_cselect_b64 s[2:3], -1, 0
	s_and_b64 s[0:1], s[0:1], s[2:3]
	s_andn2_b64 vcc, exec, s[0:1]
	s_cbranch_vccnz .LBB0_1283
	v_readlane_b32 s0, v254, 0
	s_waitcnt vmcnt(0)
	v_mbcnt_lo_u32_b32 v0, -1, 0
	s_andn2_b32 s0, s0, 63
	v_mbcnt_hi_u32_b32 v0, -1, v0
	v_or_b32_e32 v46, s0, v0
	v_readlane_b32 s0, v254, 3
	s_mov_b64 s[2:3], s[92:93]
	s_waitcnt lgkmcnt(0)
	v_readlane_b32 s4, v254, 4
	v_mov_b32_e32 v0, 0
	s_mov_b32 s12, s90
	s_mov_b32 s1, 0
	v_readfirstlane_b32 s0, v46
	s_ashr_i32 s0, s0, 6
	s_mul_i32 s0, s0, s12
	s_add_i32 s0, s4, s0
	s_add_i32 s10, s0, 0x4000
	v_mov_b32_e32 v1, 0
	s_cmpk_gt_i32 s10, 0x441f
	s_barrier
	s_barrier
	s_cbranch_scc1 .LBB0_1237
	s_load_dwordx4 s[16:19], s[2:3], 0xb8
	s_load_dwordx2 s[6:7], s[2:3], 0xe8
	v_lshlrev_b32_e32 v0, 2, v46
	v_and_b32_e32 v6, 0xfc, v0
	v_lshlrev_b32_e32 v0, 2, v6
	s_waitcnt lgkmcnt(0)
	v_mov_b32_e32 v3, s17
	v_mov_b32_e32 v2, s16
	v_mov_b32_e32 v5, s19
	v_mov_b32_e32 v4, s18
	v_lshl_add_u64 v[16:17], v[2:3], 0, v[0:1]
	v_lshl_add_u64 v[18:19], v[4:5], 0, v[0:1]
	global_load_dwordx4 v[128:131], v[16:17], off
	global_load_dwordx4 v[132:135], v[16:17], off offset:1024
	global_load_dwordx4 v[136:139], v[16:17], off offset:2048
	global_load_dwordx4 v[140:143], v[16:17], off offset:3072
	global_load_dwordx4 v[144:147], v[18:19], off
	global_load_dwordx4 v[148:151], v[18:19], off offset:1024
	global_load_dwordx4 v[152:155], v[18:19], off offset:2048
	global_load_dwordx4 v[156:159], v[18:19], off offset:3072
	v_lshlrev_b32_e32 v0, 1, v6
	v_lshl_add_u64 v[2:3], s[6:7], 0, v[0:1]
	s_mov_b64 s[8:9], 0xa700000
	s_lshl_b32 s4, s12, 3
	v_lshl_add_u64 v[20:21], v[2:3], 0, s[8:9]
	s_mov_b64 s[8:9], 0x1f400000
	v_and_b32_e32 v0, 63, v46
	v_lshl_add_u64 v[22:23], v[2:3], 0, s[8:9]
	s_mov_b64 s[8:9], 0x1bc00000
	v_lshlrev_b32_e32 v0, 3, v0
	s_ashr_i32 s11, s10, 31
	s_ashr_i32 s5, s4, 31
	v_lshl_add_u64 v[24:25], v[2:3], 0, s[8:9]
	v_lshl_add_u64 v[26:27], s[6:7], 0, v[0:1]
	s_lshl_b64 s[6:7], s[10:11], 11
	s_lshl_b64 s[8:9], s[4:5], 11
	s_lshl_b32 s22, s10, 10
	s_lshl_b32 s23, s12, 13
	s_lshl_b64 s[10:11], s[10:11], 12
	s_lshl_b64 s[12:13], s[4:5], 12
	v_lshlrev_b32_e32 v47, 2, v6
	v_mov_b32_e32 v48, 0x358637bd
	s_mov_b32 s5, 0x800000
	v_mov_b32_e32 v49, 0x3a800000
	s_branch .LBB0_1225
.LBB0_1224:
	s_nop 0
	v_mov_b32_e32 v50, v128
	v_mov_b32_e32 v51, v129
	v_mov_b32_e32 v52, v130
	v_mov_b32_e32 v53, v131
	v_pk_mul_f32 v[44:45], v[36:37], v[36:37]
	v_pk_mul_f32 v[54:55], v[40:41], v[40:41]
	v_pk_mul_f32 v[56:57], v[38:39], v[38:39]
	v_pk_mul_f32 v[58:59], v[42:43], v[42:43]
	v_mul_f32_e32 v60, v34, v34
	v_pk_mov_b32 v[64:65], v[58:59], v[56:57] op_sel:[1,0]
	v_mov_b32_e32 v59, v57
	v_pk_mov_b32 v[56:57], v[54:55], v[44:45] op_sel:[1,0]
	v_mov_b32_e32 v55, v45
	v_mul_f32_e32 v62, v32, v32
	v_mov_b32_e32 v63, 0
	v_pk_add_f32 v[58:59], v[64:65], v[58:59]
	v_pk_add_f32 v[54:55], v[56:57], v[54:55]
	v_pk_fma_f32 v[44:45], v[34:35], v[34:35], v[60:61] op_sel_hi:[1,1,0]
	v_pk_fma_f32 v[60:61], v[32:33], v[32:33], v[62:63] op_sel_hi:[1,1,0]
	v_pk_add_f32 v[56:57], v[58:59], v[58:59] op_sel_hi:[0,1]
	v_pk_add_f32 v[54:55], v[54:55], v[54:55] op_sel_hi:[0,1]
	v_mul_f32_e32 v44, v30, v30
	v_mul_f32_e32 v60, v31, v31
	v_mul_f32_e32 v56, v28, v28
	v_mul_f32_e32 v54, v29, v29
	v_pk_add_f32 v[44:45], v[44:45], v[60:61]
	v_pk_add_f32 v[54:55], v[56:57], v[54:55]
	v_mov_b32_e32 v66, 0
	v_pk_add_f32 v[44:45], v[44:45], v[54:55]
	s_add_i32 s0, s0, s4
	v_add_f32_e32 v44, v44, v45
	s_nop 1
	v_add_f32_dpp v44, v44, v44 quad_perm:[1,0,3,2] row_mask:0xf bank_mask:0xf bound_ctrl:1
	s_nop 1
	v_add_f32_dpp v44, v44, v44 quad_perm:[2,3,0,1] row_mask:0xf bank_mask:0xf bound_ctrl:1
	s_nop 1
	v_add_f32_dpp v44, v44, v44 row_half_mirror row_mask:0xf bank_mask:0xf bound_ctrl:1
	s_nop 1
	v_add_f32_dpp v44, v44, v44 row_mirror row_mask:0xf bank_mask:0xf bound_ctrl:1
	s_nop 1
	v_mov_b32_dpp v63, v44 row_bcast:15 row_mask:0xa bank_mask:0xf
	v_add_f32_e32 v44, v44, v63
	s_nop 1
	v_mov_b32_dpp v66, v44 row_bcast:31 row_mask:0xc bank_mask:0xf
	v_add_f32_e32 v44, v44, v66
	s_nop 0
	v_readlane_b32 s14, v44, 63
	s_nop 1
	v_fma_f32 v44, s14, v49, v48
	v_mul_f32_e32 v45, 0x4b800000, v44
	v_cmp_gt_f32_e32 vcc, s5, v44
	s_nop 1
	v_cndmask_b32_e32 v44, v44, v45, vcc
	v_rsq_f32_e32 v54, v44
	v_lshl_add_u64 v[44:45], v[22:23], 0, s[16:17]
	v_mul_f32_e32 v55, 0x45800000, v54
	v_cndmask_b32_e32 v54, v54, v55, vcc
	v_pk_mul_f32 v[42:43], v[42:43], v[54:55] op_sel_hi:[1,0]
	v_pk_mul_f32 v[38:39], v[38:39], v[54:55] op_sel_hi:[1,0]
	v_pk_mul_f32 v[40:41], v[40:41], v[54:55] op_sel_hi:[1,0]
	v_pk_mul_f32 v[36:37], v[36:37], v[54:55] op_sel_hi:[1,0]
	v_pk_mul_f32 v[34:35], v[34:35], v[54:55] op_sel_hi:[1,0]
	v_pk_mul_f32 v[32:33], v[32:33], v[54:55] op_sel_hi:[1,0]
	v_pk_mul_f32 v[30:31], v[30:31], v[54:55] op_sel_hi:[1,0]
	v_pk_mul_f32 v[28:29], v[28:29], v[54:55] op_sel_hi:[1,0]
	s_waitcnt vmcnt(0)
	v_pk_fma_f32 v[38:39], v[52:53], v[38:39], v[14:15]
	v_pk_fma_f32 v[42:43], v[50:51], v[42:43], v[12:13]
	v_cvt_pk_bf16_f32 v13, v38, v39
	v_cvt_pk_bf16_f32 v12, v42, v43
	global_store_dwordx2 v[44:45], v[12:13], off
	s_nop 0
	v_mov_b32_e32 v12, v132
	v_mov_b32_e32 v13, v133
	v_mov_b32_e32 v14, v134
	v_mov_b32_e32 v15, v135
	s_nop 0
	v_pk_fma_f32 v[14:15], v[14:15], v[36:37], v[10:11]
	v_pk_fma_f32 v[12:13], v[12:13], v[40:41], v[8:9]
	v_cvt_pk_bf16_f32 v9, v14, v15
	v_cvt_pk_bf16_f32 v8, v12, v13
	global_store_dwordx2 v[44:45], v[8:9], off offset:512
	s_nop 0
	v_mov_b32_e32 v8, v136
	v_mov_b32_e32 v9, v137
	v_mov_b32_e32 v10, v138
	v_mov_b32_e32 v11, v139
	v_mov_b32_e32 v36, 0
	v_mov_b32_e32 v37, 0
	s_nop 0
	v_pk_fma_f32 v[10:11], v[10:11], v[32:33], v[6:7]
	v_pk_fma_f32 v[8:9], v[8:9], v[34:35], v[4:5]
	v_cvt_pk_bf16_f32 v5, v10, v11
	v_cvt_pk_bf16_f32 v4, v8, v9
	global_store_dwordx2 v[44:45], v[4:5], off offset:1024
	s_nop 0
	v_mov_b32_e32 v4, v140
	v_mov_b32_e32 v5, v141
	v_mov_b32_e32 v6, v142
	v_mov_b32_e32 v7, v143
	s_nop 0
	v_pk_fma_f32 v[6:7], v[6:7], v[28:29], v[2:3]
	v_pk_fma_f32 v[4:5], v[4:5], v[30:31], v[0:1]
	v_cvt_pk_bf16_f32 v1, v6, v7
	v_cvt_pk_bf16_f32 v0, v4, v5
	global_store_dwordx2 v[44:45], v[0:1], off offset:1536
	s_nop 0
	v_mov_b32_e32 v0, v144
	v_mov_b32_e32 v1, v145
	v_mov_b32_e32 v2, v146
	v_mov_b32_e32 v3, v147
	v_pk_mul_f32 v[28:29], v[38:39], v[38:39]
	v_pk_mul_f32 v[30:31], v[42:43], v[42:43]
	s_nop 0
	v_pk_mov_b32 v[32:33], v[30:31], v[28:29] op_sel:[1,0]
	v_mov_b32_e32 v31, v29
	v_pk_add_f32 v[28:29], v[32:33], v[30:31]
	v_pk_mul_f32 v[30:31], v[12:13], v[12:13]
	v_pk_mul_f32 v[32:33], v[14:15], v[14:15]
	v_pk_add_f32 v[28:29], v[28:29], v[28:29] op_sel_hi:[0,1]
	v_pk_mov_b32 v[34:35], v[30:31], v[32:33] op_sel:[1,0]
	v_mov_b32_e32 v31, v33
	v_pk_add_f32 v[30:31], v[34:35], v[30:31]
	v_mul_f32_e32 v28, v8, v8
	v_pk_add_f32 v[30:31], v[30:31], v[30:31] op_sel_hi:[0,1]
	v_mul_f32_e32 v30, v10, v10
	v_pk_fma_f32 v[32:33], v[8:9], v[8:9], v[28:29] op_sel_hi:[1,1,0]
	v_pk_fma_f32 v[34:35], v[10:11], v[10:11], v[30:31] op_sel_hi:[1,1,0]
	v_mul_f32_e32 v32, v4, v4
	v_mul_f32_e32 v34, v5, v5
	v_mul_f32_e32 v28, v6, v6
	v_mul_f32_e32 v30, v7, v7
	v_pk_add_f32 v[32:33], v[32:33], v[34:35]
	v_pk_add_f32 v[28:29], v[28:29], v[30:31]
	s_nop 0
	v_pk_add_f32 v[28:29], v[32:33], v[28:29]
	s_nop 0
	v_add_f32_e32 v28, v28, v29
	s_nop 1
	v_add_f32_dpp v28, v28, v28 quad_perm:[1,0,3,2] row_mask:0xf bank_mask:0xf bound_ctrl:1
	s_nop 1
	v_add_f32_dpp v28, v28, v28 quad_perm:[2,3,0,1] row_mask:0xf bank_mask:0xf bound_ctrl:1
	s_nop 1
	v_add_f32_dpp v28, v28, v28 row_half_mirror row_mask:0xf bank_mask:0xf bound_ctrl:1
	s_nop 1
	v_add_f32_dpp v28, v28, v28 row_mirror row_mask:0xf bank_mask:0xf bound_ctrl:1
	s_nop 1
	v_mov_b32_dpp v36, v28 row_bcast:15 row_mask:0xa bank_mask:0xf
	v_add_f32_e32 v28, v28, v36
	s_nop 1
	v_mov_b32_dpp v37, v28 row_bcast:31 row_mask:0xc bank_mask:0xf
	v_add_f32_e32 v28, v28, v37
	s_nop 0
	v_readlane_b32 s14, v28, 63
	s_nop 1
	v_fma_f32 v28, s14, v49, v48
	v_mul_f32_e32 v29, 0x4b800000, v28
	v_cmp_gt_f32_e32 vcc, s5, v28
	s_add_i32 s14, s0, 0x4000
	s_add_u32 s6, s6, s8
	v_cndmask_b32_e32 v28, v28, v29, vcc
	v_rsq_f32_e32 v30, v28
	v_lshl_add_u64 v[28:29], v[20:21], 0, s[16:17]
	s_addc_u32 s7, s7, s9
	s_add_i32 s22, s22, s23
	v_mul_f32_e32 v31, 0x45800000, v30
	v_cndmask_b32_e32 v30, v30, v31, vcc
	v_pk_mul_f32 v[32:33], v[42:43], v[30:31] op_sel_hi:[1,0]
	v_pk_mul_f32 v[34:35], v[38:39], v[30:31] op_sel_hi:[1,0]
	v_pk_mul_f32 v[12:13], v[12:13], v[30:31] op_sel_hi:[1,0]
	v_pk_mul_f32 v[14:15], v[14:15], v[30:31] op_sel_hi:[1,0]
	v_pk_mul_f32 v[8:9], v[8:9], v[30:31] op_sel_hi:[1,0]
	v_pk_mul_f32 v[10:11], v[10:11], v[30:31] op_sel_hi:[1,0]
	s_add_u32 s10, s10, s12
	v_pk_mul_f32 v[4:5], v[4:5], v[30:31] op_sel_hi:[1,0]
	v_pk_mul_f32 v[6:7], v[6:7], v[30:31] op_sel_hi:[1,0]
	s_addc_u32 s11, s11, s13
	s_cmpk_lt_i32 s14, 0x4420
	s_nop 0
	v_pk_mul_f32 v[2:3], v[2:3], v[34:35]
	v_pk_mul_f32 v[0:1], v[0:1], v[32:33]
	s_nop 0
	v_cvt_pk_bf16_f32 v0, v0, v1
	v_cvt_pk_bf16_f32 v1, v2, v3
	global_store_dwordx2 v[28:29], v[0:1], off
	s_nop 0
	v_mov_b32_e32 v0, v148
	v_mov_b32_e32 v1, v149
	v_mov_b32_e32 v2, v150
	v_mov_b32_e32 v3, v151
	s_nop 0
	v_pk_mul_f32 v[2:3], v[2:3], v[14:15]
	v_pk_mul_f32 v[0:1], v[0:1], v[12:13]
	s_nop 0
	v_cvt_pk_bf16_f32 v0, v0, v1
	v_cvt_pk_bf16_f32 v1, v2, v3
	global_store_dwordx2 v[28:29], v[0:1], off offset:512
	s_nop 0
	v_mov_b32_e32 v0, v152
	v_mov_b32_e32 v1, v153
	v_mov_b32_e32 v2, v154
	v_mov_b32_e32 v3, v155
	s_nop 0
	v_pk_mul_f32 v[2:3], v[2:3], v[10:11]
	v_pk_mul_f32 v[0:1], v[0:1], v[8:9]
	s_nop 0
	v_cvt_pk_bf16_f32 v0, v0, v1
	v_cvt_pk_bf16_f32 v1, v2, v3
	global_store_dwordx2 v[28:29], v[0:1], off offset:1024
	s_nop 0
	v_mov_b32_e32 v0, v156
	v_mov_b32_e32 v1, v157
	v_mov_b32_e32 v2, v158
	v_mov_b32_e32 v3, v159
	s_nop 0
	v_pk_mul_f32 v[2:3], v[2:3], v[6:7]
	v_pk_mul_f32 v[0:1], v[0:1], v[4:5]
	s_nop 0
	v_cvt_pk_bf16_f32 v0, v0, v1
	v_cvt_pk_bf16_f32 v1, v2, v3
	global_store_dwordx2 v[28:29], v[0:1], off offset:1536
	s_cbranch_scc0 .LBB0_1237

.LBB0_1527:
	s_cmp_lt_i32 s88, 10
	s_cselect_b64 s[0:1], -1, 0
	s_cmp_gt_i32 s89, 9
	s_cselect_b64 s[2:3], -1, 0
	s_and_b64 s[0:1], s[0:1], s[2:3]
	s_andn2_b64 vcc, exec, s[0:1]
	s_cbranch_vccnz .LBB0_1609
	v_readlane_b32 s0, v254, 0
	s_waitcnt vmcnt(0)
	v_mbcnt_lo_u32_b32 v0, -1, 0
	s_andn2_b32 s0, s0, 63
	v_mbcnt_hi_u32_b32 v0, -1, v0
	v_or_b32_e32 v4, s0, v0
	v_mov_b32_e32 v74, 0
	s_mov_b64 s[2:3], s[92:93]
	v_readlane_b32 s16, v254, 4
	s_mov_b32 s17, s90
	v_readlane_b32 s0, v254, 3
	s_waitcnt lgkmcnt(0)
	s_load_dwordx2 s[4:5], s[2:3], 0xe8
	s_movk_i32 s0, 0x3000
	v_readfirstlane_b32 s12, v4
	v_cmp_gt_i32_e32 vcc, s0, v4
	s_waitcnt lgkmcnt(0)
	s_barrier
	s_and_saveexec_b64 s[0:1], vcc
	s_cbranch_execz .LBB0_1536
	s_load_dwordx2 s[6:7], s[2:3], 0x48
	s_movk_i32 s8, 0x3830
	v_mul_u32_u24_e32 v0, s8, v4
	v_add_u32_e32 v1, 0x200, v4
	v_mul_u32_u24_e32 v1, s8, v1
	v_add_u32_e32 v0, 0x2810, v0
	v_add_u32_e32 v1, 0x2810, v1
	s_waitcnt lgkmcnt(0)
	s_add_u32 s6, s6, 0xe0c000
	s_addc_u32 s7, s7, 0
	global_load_dwordx4 v[128:131], v0, s[6:7] offset:-2064
	global_load_dwordx4 v[132:135], v0, s[6:7] offset:-2048
	global_load_dwordx4 v[136:139], v0, s[6:7] offset:2064
	global_load_dwordx4 v[140:143], v1, s[6:7] offset:-2064
	global_load_dwordx4 v[144:147], v1, s[6:7] offset:-2048
	global_load_dwordx4 v[148:151], v1, s[6:7] offset:2064
	v_lshl_add_u32 v2, v4, 2, v74
	s_waitcnt vmcnt(0)
	ds_write_b32 v2, v128 offset:0
	ds_write_b32 v2, v129 offset:4096
	ds_write_b32 v2, v130 offset:8192
	ds_write_b32 v2, v131 offset:12288
	ds_write_b32 v2, v132 offset:16384
	ds_write_b32 v2, v133 offset:20480
	ds_write_b32 v2, v134 offset:24576
	ds_write_b32 v2, v135 offset:28672
	ds_write_b32 v2, v136 offset:32768
	ds_write_b32 v2, v137 offset:36864
	ds_write_b32 v2, v138 offset:40960
	ds_write_b32 v2, v139 offset:45056
	ds_write_b32 v2, v140 offset:2048
	ds_write_b32 v2, v141 offset:6144
	ds_write_b32 v2, v142 offset:10240
	ds_write_b32 v2, v143 offset:14336
	ds_write_b32 v2, v144 offset:18432
	ds_write_b32 v2, v145 offset:22528
	ds_write_b32 v2, v146 offset:26624
	ds_write_b32 v2, v147 offset:30720
	ds_write_b32 v2, v148 offset:34816
	ds_write_b32 v2, v149 offset:38912
	ds_write_b32 v2, v150 offset:43008
	ds_write_b32 v2, v151 offset:47104
.LBB0_1536:
	s_or_b64 exec, exec, s[0:1]
	s_ashr_i32 s18, s12, 6
	v_mov_b32_e32 v0, s17
	v_lshlrev_b32_e64 v1, 3, s17
	v_mul_lo_u32 v0, s18, v0
	v_readfirstlane_b32 s0, v1
	v_mov_b32_e32 v1, 0x4000
	v_add3_u32 v0, s16, v0, v1
	s_movk_i32 s1, 0x441f
	v_cmp_lt_i32_e32 vcc, s1, v0
	s_and_b64 s[6:7], vcc, exec
	v_and_b32_e32 v5, 63, v4
	v_readfirstlane_b32 s6, v0
	s_waitcnt lgkmcnt(0)
	s_barrier
	s_cbranch_scc1 .LBB0_1553
	s_load_dwordx2 s[8:9], s[2:3], 0xb0
	s_load_dwordx2 s[10:11], s[2:3], 0xc8
	v_lshlrev_b32_e32 v10, 3, v5
	v_mov_b32_e32 v11, 0
	v_lshl_add_u64 v[12:13], s[4:5], 0, v[10:11]
	s_mov_b64 s[2:3], 0xca00000
	v_lshlrev_b32_e32 v10, 4, v5
	v_lshl_add_u64 v[0:1], v[12:13], 0, s[2:3]
	s_waitcnt lgkmcnt(0)
	v_lshl_add_u64 v[2:3], s[10:11], 0, v[10:11]
	v_lshl_add_u64 v[6:7], s[8:9], 0, v[10:11]
	s_mov_b64 s[2:3], 0x1000
	s_mov_b64 s[10:11], 0x1f400000
	v_lshl_add_u64 v[6:7], v[6:7], 0, s[2:3]
	global_load_dwordx4 v[128:131], v[2:3], off
	global_load_dwordx4 v[132:135], v[2:3], off offset:1024
	global_load_dwordx4 v[136:139], v[2:3], off offset:2048
	global_load_dwordx4 v[140:143], v[2:3], off offset:3072
	global_load_dwordx4 v[144:147], v[6:7], off
	global_load_dwordx4 v[148:151], v[6:7], off offset:1024
	global_load_dwordx4 v[152:155], v[6:7], off offset:2048
	global_load_dwordx4 v[156:159], v[6:7], off offset:3072
	s_mov_b64 s[2:3], 0xa700000
	v_add_u32_e32 v75, v74, v10
	v_lshl_add_u64 v[10:11], v[12:13], 0, s[10:11]
	s_mov_b64 s[10:11], 0x1bc00000
	s_ashr_i32 s7, s6, 31
	v_lshl_add_u64 v[8:9], v[12:13], 0, s[2:3]
	v_lshl_add_u64 v[12:13], v[12:13], 0, s[10:11]
	s_lshl_b64 s[10:11], s[6:7], 6
	s_add_u32 s19, s4, s10
	s_addc_u32 s20, s5, s11
	s_ashr_i32 s1, s0, 31
	s_mov_b32 s9, 0
	v_cmp_eq_u32_e64 s[2:3], 0, v5
	s_lshl_b64 s[10:11], s[0:1], 6
	v_mov_b32_e32 v76, 0x358637bd
	s_mov_b32 s1, 0x800000
	v_mov_b32_e32 v77, 0x100000
	v_mov_b32_e32 v78, 0x3a800000
	s_branch .LBB0_1539

.LBB0_1543:
	s_nop 0
	v_mov_b32_e32 v40, v128
	v_mov_b32_e32 v41, v129
	v_mov_b32_e32 v42, v130
	v_mov_b32_e32 v43, v131
	v_pk_mul_f32 v[46:47], v[32:33], v[32:33]
	v_pk_mul_f32 v[48:49], v[34:35], v[34:35]
	v_pk_mul_f32 v[50:51], v[36:37], v[36:37]
	v_pk_mul_f32 v[52:53], v[38:39], v[38:39]
	v_mul_f32_e32 v54, v30, v30
	v_pk_mov_b32 v[58:59], v[52:53], v[50:51] op_sel:[1,0]
	v_mov_b32_e32 v53, v51
	v_pk_mov_b32 v[50:51], v[48:49], v[46:47] op_sel:[1,0]
	v_mov_b32_e32 v49, v47
	v_mul_f32_e32 v56, v28, v28
	v_mov_b32_e32 v57, 0
	v_pk_add_f32 v[52:53], v[58:59], v[52:53]
	v_pk_add_f32 v[48:49], v[50:51], v[48:49]
	v_pk_fma_f32 v[46:47], v[30:31], v[30:31], v[54:55] op_sel_hi:[1,1,0]
	v_pk_fma_f32 v[54:55], v[28:29], v[28:29], v[56:57] op_sel_hi:[1,1,0]
	v_pk_add_f32 v[50:51], v[52:53], v[52:53] op_sel_hi:[0,1]
	v_pk_add_f32 v[48:49], v[48:49], v[48:49] op_sel_hi:[0,1]
	v_mul_f32_e32 v46, v26, v26
	v_mul_f32_e32 v54, v27, v27
	v_mul_f32_e32 v50, v24, v24
	v_mul_f32_e32 v48, v25, v25
	v_pk_add_f32 v[46:47], v[46:47], v[54:55]
	v_pk_add_f32 v[48:49], v[50:51], v[48:49]
	v_mov_b32_e32 v45, 0
	v_pk_add_f32 v[46:47], v[46:47], v[48:49]
	s_waitcnt vmcnt(4)
	v_lshlrev_b32_e32 v44, 16, v22
	v_add_f32_e32 v46, v46, v47
	s_nop 1
	v_add_f32_dpp v46, v46, v46 quad_perm:[1,0,3,2] row_mask:0xf bank_mask:0xf bound_ctrl:1
	s_nop 1
	v_add_f32_dpp v46, v46, v46 quad_perm:[2,3,0,1] row_mask:0xf bank_mask:0xf bound_ctrl:1
	s_nop 1
	v_add_f32_dpp v46, v46, v46 row_half_mirror row_mask:0xf bank_mask:0xf bound_ctrl:1
	s_nop 1
	v_add_f32_dpp v46, v46, v46 row_mirror row_mask:0xf bank_mask:0xf bound_ctrl:1
	s_nop 1
	v_mov_b32_dpp v45, v46 row_bcast:15 row_mask:0xa bank_mask:0xf
	v_add_f32_e32 v45, v46, v45
	s_nop 1
	v_mov_b32_dpp v57, v45 row_bcast:31 row_mask:0xc bank_mask:0xf
	v_add_f32_e32 v45, v45, v57
	s_nop 0
	v_readlane_b32 s7, v45, 63
	s_nop 1
	v_fma_f32 v45, s7, v78, v76
	v_mul_f32_e32 v46, 0x4b800000, v45
	v_cmp_gt_f32_e32 vcc, s1, v45
	s_nop 1
	v_cndmask_b32_e32 v45, v45, v46, vcc
	v_rsq_f32_e32 v46, v45
	v_and_b32_e32 v45, 0xffff0000, v22
	v_lshlrev_b32_e32 v22, 16, v23
	v_and_b32_e32 v23, 0xffff0000, v23
	v_mul_f32_e32 v47, 0x45800000, v46
	v_cndmask_b32_e32 v46, v46, v47, vcc
	v_pk_mul_f32 v[38:39], v[38:39], v[46:47] op_sel_hi:[1,0]
	v_pk_mul_f32 v[36:37], v[36:37], v[46:47] op_sel_hi:[1,0]
	v_pk_mul_f32 v[34:35], v[34:35], v[46:47] op_sel_hi:[1,0]
	v_pk_mul_f32 v[32:33], v[32:33], v[46:47] op_sel_hi:[1,0]
	v_pk_mul_f32 v[30:31], v[30:31], v[46:47] op_sel_hi:[1,0]
	v_pk_mul_f32 v[28:29], v[28:29], v[46:47] op_sel_hi:[1,0]
	v_pk_mul_f32 v[26:27], v[26:27], v[46:47] op_sel_hi:[1,0]
	v_pk_mul_f32 v[24:25], v[24:25], v[46:47] op_sel_hi:[1,0]
	s_waitcnt vmcnt(0)
	v_pk_fma_f32 v[42:43], v[42:43], v[36:37], v[22:23]
	v_pk_fma_f32 v[40:41], v[40:41], v[38:39], v[44:45]
	v_cvt_pk_bf16_f32 v23, v42, v43
	v_cvt_pk_bf16_f32 v22, v40, v41
	global_store_dwordx2 v[14:15], v[22:23], off
	s_nop 0
	v_mov_b32_e32 v36, v132
	v_mov_b32_e32 v37, v133
	v_mov_b32_e32 v38, v134
	v_mov_b32_e32 v39, v135
	v_lshlrev_b32_e32 v22, 16, v20
	v_and_b32_e32 v23, 0xffff0000, v20
	v_lshlrev_b32_e32 v20, 16, v21
	v_and_b32_e32 v21, 0xffff0000, v21
	v_lshl_add_u64 v[44:45], v[8:9], 0, s[12:13]
	s_mov_b64 s[12:13], 0
	s_nop 0
	v_pk_fma_f32 v[32:33], v[38:39], v[32:33], v[20:21]
	v_pk_fma_f32 v[34:35], v[36:37], v[34:35], v[22:23]
	v_cvt_pk_bf16_f32 v21, v32, v33
	v_cvt_pk_bf16_f32 v20, v34, v35
	global_store_dwordx2 v[14:15], v[20:21], off offset:512
	s_nop 0
	v_mov_b32_e32 v20, v136
	v_mov_b32_e32 v21, v137
	v_mov_b32_e32 v22, v138
	v_mov_b32_e32 v23, v139
	v_lshlrev_b32_e32 v36, 16, v18
	v_and_b32_e32 v37, 0xffff0000, v18
	v_lshlrev_b32_e32 v18, 16, v19
	v_and_b32_e32 v19, 0xffff0000, v19
	s_nop 0
	v_pk_fma_f32 v[28:29], v[22:23], v[28:29], v[18:19]
	v_pk_fma_f32 v[30:31], v[20:21], v[30:31], v[36:37]
	v_cvt_pk_bf16_f32 v19, v28, v29
	v_cvt_pk_bf16_f32 v18, v30, v31
	global_store_dwordx2 v[14:15], v[18:19], off offset:1024
	s_nop 0
	v_mov_b32_e32 v18, v140
	v_mov_b32_e32 v19, v141
	v_mov_b32_e32 v20, v142
	v_mov_b32_e32 v21, v143
	v_lshlrev_b32_e32 v22, 16, v16
	v_and_b32_e32 v23, 0xffff0000, v16
	v_lshlrev_b32_e32 v16, 16, v17
	v_and_b32_e32 v17, 0xffff0000, v17
	s_nop 0
	v_pk_fma_f32 v[36:37], v[20:21], v[24:25], v[16:17]
	v_pk_fma_f32 v[38:39], v[18:19], v[26:27], v[22:23]
	v_cvt_pk_bf16_f32 v17, v36, v37
	v_cvt_pk_bf16_f32 v16, v38, v39
	global_store_dwordx2 v[14:15], v[16:17], off offset:1536
	s_nop 0
	v_mov_b32_e32 v16, v144
	v_mov_b32_e32 v17, v145
	v_mov_b32_e32 v18, v146
	v_mov_b32_e32 v19, v147
	v_pk_mul_f32 v[14:15], v[42:43], v[42:43]
	v_pk_mul_f32 v[20:21], v[40:41], v[40:41]
	v_mov_b32_e32 v26, 0
	v_pk_mov_b32 v[22:23], v[20:21], v[14:15] op_sel:[1,0]
	v_mov_b32_e32 v21, v15
	v_pk_add_f32 v[14:15], v[22:23], v[20:21]
	v_pk_mul_f32 v[20:21], v[34:35], v[34:35]
	v_pk_mul_f32 v[22:23], v[32:33], v[32:33]
	v_pk_add_f32 v[14:15], v[14:15], v[14:15] op_sel_hi:[0,1]
	v_pk_mov_b32 v[24:25], v[20:21], v[22:23] op_sel:[1,0]
	v_mov_b32_e32 v21, v23
	v_pk_add_f32 v[20:21], v[24:25], v[20:21]
	v_mul_f32_e32 v14, v30, v30
	v_pk_add_f32 v[20:21], v[20:21], v[20:21] op_sel_hi:[0,1]
	v_mul_f32_e32 v20, v28, v28
	v_pk_fma_f32 v[22:23], v[30:31], v[30:31], v[14:15] op_sel_hi:[1,1,0]
	v_pk_fma_f32 v[24:25], v[28:29], v[28:29], v[20:21] op_sel_hi:[1,1,0]
	v_mul_f32_e32 v22, v38, v38
	v_mul_f32_e32 v24, v39, v39
	v_mul_f32_e32 v14, v36, v36
	v_mul_f32_e32 v20, v37, v37
	v_pk_add_f32 v[22:23], v[22:23], v[24:25]
	v_pk_add_f32 v[14:15], v[14:15], v[20:21]
	v_mov_b32_e32 v27, 0
	v_pk_add_f32 v[14:15], v[22:23], v[14:15]
	s_nop 0
	v_add_f32_e32 v14, v14, v15
	s_nop 1
	v_add_f32_dpp v14, v14, v14 quad_perm:[1,0,3,2] row_mask:0xf bank_mask:0xf bound_ctrl:1
	s_nop 1
	v_add_f32_dpp v14, v14, v14 quad_perm:[2,3,0,1] row_mask:0xf bank_mask:0xf bound_ctrl:1
	s_nop 1
	v_add_f32_dpp v14, v14, v14 row_half_mirror row_mask:0xf bank_mask:0xf bound_ctrl:1
	s_nop 1
	v_add_f32_dpp v14, v14, v14 row_mirror row_mask:0xf bank_mask:0xf bound_ctrl:1
	s_nop 1
	v_mov_b32_dpp v26, v14 row_bcast:15 row_mask:0xa bank_mask:0xf
	v_add_f32_e32 v14, v14, v26
	s_nop 1
	v_mov_b32_dpp v27, v14 row_bcast:31 row_mask:0xc bank_mask:0xf
	v_add_f32_e32 v14, v14, v27
	s_nop 0
	v_readlane_b32 s7, v14, 63
	s_nop 1
	v_fma_f32 v14, s7, v78, v76
	v_mul_f32_e32 v15, 0x4b800000, v14
	v_cmp_gt_f32_e32 vcc, s1, v14
	s_nop 1
	v_cndmask_b32_e32 v14, v14, v15, vcc
	v_rsq_f32_e32 v14, v14
	s_nop 0
	v_mul_f32_e32 v15, 0x45800000, v14
	v_cndmask_b32_e32 v46, v14, v15, vcc
	v_pk_mul_f32 v[20:21], v[40:41], v[46:47] op_sel_hi:[1,0]
	v_pk_mul_f32 v[14:15], v[42:43], v[46:47] op_sel_hi:[1,0]
	v_pk_mul_f32 v[22:23], v[32:33], v[46:47] op_sel_hi:[1,0]
	v_pk_mul_f32 v[24:25], v[34:35], v[46:47] op_sel_hi:[1,0]
	v_pk_mul_f32 v[26:27], v[28:29], v[46:47] op_sel_hi:[1,0]
	v_pk_mul_f32 v[28:29], v[30:31], v[46:47] op_sel_hi:[1,0]
	v_pk_mul_f32 v[30:31], v[36:37], v[46:47] op_sel_hi:[1,0]
	v_pk_mul_f32 v[32:33], v[38:39], v[46:47] op_sel_hi:[1,0]
	s_nop 0
	v_pk_mul_f32 v[14:15], v[18:19], v[14:15]
	v_pk_mul_f32 v[16:17], v[16:17], v[20:21]
	v_cvt_pk_bf16_f32 v19, v14, v15
	v_cvt_pk_bf16_f32 v18, v16, v17
	global_store_dwordx2 v[44:45], v[18:19], off
	s_nop 0
	v_mov_b32_e32 v18, v148
	v_mov_b32_e32 v19, v149
	v_mov_b32_e32 v20, v150
	v_mov_b32_e32 v21, v151
	s_nop 0
	v_pk_mul_f32 v[18:19], v[18:19], v[24:25]
	v_pk_mul_f32 v[20:21], v[20:21], v[22:23]
	v_cvt_pk_bf16_f32 v22, v18, v19
	v_cvt_pk_bf16_f32 v23, v20, v21
	global_store_dwordx2 v[44:45], v[22:23], off offset:512
	s_nop 0
	v_mov_b32_e32 v22, v152
	v_mov_b32_e32 v23, v153
	v_mov_b32_e32 v24, v154
	v_mov_b32_e32 v25, v155
	s_nop 0
	v_pk_mul_f32 v[22:23], v[22:23], v[28:29]
	v_pk_mul_f32 v[24:25], v[24:25], v[26:27]
	v_cvt_pk_bf16_f32 v26, v22, v23
	v_cvt_pk_bf16_f32 v27, v24, v25
	global_store_dwordx2 v[44:45], v[26:27], off offset:1024
	s_nop 0
	v_mov_b32_e32 v26, v156
	v_mov_b32_e32 v27, v157
	v_mov_b32_e32 v28, v158
	v_mov_b32_e32 v29, v159
	s_nop 0
	v_pk_mul_f32 v[26:27], v[26:27], v[32:33]
	v_pk_mul_f32 v[28:29], v[28:29], v[30:31]
	v_cvt_pk_bf16_f32 v30, v26, v27
	v_cvt_pk_bf16_f32 v31, v28, v29
	global_store_dwordx2 v[44:45], v[30:31], off offset:1536
	v_mov_b32_e32 v30, v75
	s_branch .LBB0_1545

.LBB0_2657:
	s_cmp_lt_i32 s88, 16
	s_cselect_b64 s[0:1], -1, 0
	s_cmp_gt_i32 s89, 15
	s_cselect_b64 s[2:3], -1, 0
	s_and_b64 s[0:1], s[0:1], s[2:3]
	s_andn2_b64 vcc, exec, s[0:1]
	s_cbranch_vccnz .LBB0_2711
	v_readlane_b32 s0, v254, 0
	s_waitcnt vmcnt(0)
	v_mbcnt_lo_u32_b32 v0, -1, 0
	s_andn2_b32 s0, s0, 63
	v_mbcnt_hi_u32_b32 v0, -1, v0
	v_or_b32_e32 v40, s0, v0
	s_waitcnt lgkmcnt(0)
	s_mov_b32 s5, s90
	v_readlane_b32 s0, v254, 3
	s_mov_b64 s[2:3], s[92:93]
	v_readlane_b32 s4, v254, 4
	v_mov_b32_e32 v0, 0
	s_mov_b32 s1, 0
	v_readfirstlane_b32 s0, v40
	s_ashr_i32 s0, s0, 6
	s_mul_i32 s0, s0, s5
	s_add_i32 s0, s4, s0
	s_add_i32 s4, s0, 0x4000
	v_mov_b32_e32 v11, 0
	s_cmpk_gt_i32 s4, 0x441f
	s_barrier
	s_barrier
	s_cbranch_scc1 .LBB0_2665
	s_load_dwordx4 s[8:11], s[2:3], 0xb8
	s_load_dwordx2 s[6:7], s[2:3], 0xe8
	v_lshlrev_b32_e32 v4, 2, v40
	v_and_b32_e32 v4, 0xfc, v4
	v_lshlrev_b32_e32 v10, 2, v4
	s_waitcnt lgkmcnt(0)
	v_mov_b32_e32 v1, s9
	v_mov_b32_e32 v0, s8
	v_mov_b32_e32 v3, s11
	v_mov_b32_e32 v2, s10
	v_lshl_add_u64 v[0:1], v[0:1], 0, v[10:11]
	s_mov_b64 s[8:9], 0x1000
	v_lshl_add_u64 v[2:3], v[2:3], 0, v[10:11]
	v_lshlrev_b32_e32 v10, 1, v4
	v_lshl_add_u64 v[0:1], v[0:1], 0, s[8:9]
	v_lshl_add_u64 v[2:3], v[2:3], 0, s[8:9]
	global_load_dwordx4 v[128:131], v[0:1], off
	global_load_dwordx4 v[132:135], v[0:1], off offset:1024
	global_load_dwordx4 v[136:139], v[0:1], off offset:2048
	global_load_dwordx4 v[140:143], v[0:1], off offset:3072
	global_load_dwordx4 v[144:147], v[2:3], off
	global_load_dwordx4 v[148:151], v[2:3], off offset:1024
	global_load_dwordx4 v[152:155], v[2:3], off offset:2048
	global_load_dwordx4 v[156:159], v[2:3], off offset:3072
	v_lshl_add_u64 v[8:9], s[6:7], 0, v[10:11]
	s_mov_b64 s[8:9], 0xa700000
	s_lshl_b32 s2, s5, 3
	v_lshl_add_u64 v[4:5], v[8:9], 0, s[8:9]
	s_mov_b64 s[8:9], 0x1f400000
	v_and_b32_e32 v10, 63, v40
	v_lshl_add_u64 v[6:7], v[8:9], 0, s[8:9]
	s_mov_b64 s[8:9], 0x1bc00000
	v_lshlrev_b32_e32 v10, 3, v10
	s_ashr_i32 s5, s4, 31
	s_ashr_i32 s3, s2, 31
	v_lshl_add_u64 v[8:9], v[8:9], 0, s[8:9]
	v_lshl_add_u64 v[10:11], s[6:7], 0, v[10:11]
	s_lshl_b64 s[4:5], s[4:5], 11
	s_lshl_b64 s[6:7], s[2:3], 11
	v_mov_b32_e32 v41, 0x358637bd
	s_mov_b32 s3, 0x800000
	v_mov_b32_e32 v42, 0x3a800000
	s_branch .LBB0_2661
.LBB0_2660:
	s_nop 0
	v_mov_b32_e32 v44, v128
	v_mov_b32_e32 v45, v129
	v_mov_b32_e32 v46, v130
	v_mov_b32_e32 v47, v131
	v_pk_mul_f32 v[38:39], v[30:31], v[30:31]
	v_pk_mul_f32 v[48:49], v[32:33], v[32:33]
	v_pk_mul_f32 v[50:51], v[34:35], v[34:35]
	v_pk_mul_f32 v[52:53], v[36:37], v[36:37]
	s_waitcnt vmcnt(4)
	v_lshlrev_b32_e32 v20, 16, v18
	v_pk_mov_b32 v[56:57], v[52:53], v[50:51] op_sel:[1,0]
	v_mov_b32_e32 v53, v51
	v_pk_mov_b32 v[50:51], v[48:49], v[38:39] op_sel:[1,0]
	v_mov_b32_e32 v49, v39
	v_and_b32_e32 v21, 0xffff0000, v18
	v_mul_f32_e32 v18, v28, v28
	v_mul_f32_e32 v54, v26, v26
	v_pk_add_f32 v[52:53], v[56:57], v[52:53]
	v_pk_add_f32 v[48:49], v[50:51], v[48:49]
	v_pk_fma_f32 v[38:39], v[28:29], v[28:29], v[18:19] op_sel_hi:[1,1,0]
	v_pk_fma_f32 v[54:55], v[26:27], v[26:27], v[54:55] op_sel_hi:[1,1,0]
	v_pk_add_f32 v[50:51], v[52:53], v[52:53] op_sel_hi:[0,1]
	v_pk_add_f32 v[48:49], v[48:49], v[48:49] op_sel_hi:[0,1]
	v_mul_f32_e32 v38, v24, v24
	v_mul_f32_e32 v54, v25, v25
	v_mul_f32_e32 v50, v22, v22
	v_mul_f32_e32 v48, v23, v23
	v_pk_add_f32 v[38:39], v[38:39], v[54:55]
	v_pk_add_f32 v[48:49], v[50:51], v[48:49]
	v_mov_b32_e32 v43, 0
	v_pk_add_f32 v[38:39], v[38:39], v[48:49]
	v_mov_b32_e32 v58, 0
	v_add_f32_e32 v18, v38, v39
	s_add_i32 s0, s0, s2
	s_nop 0
	v_add_f32_dpp v18, v18, v18 quad_perm:[1,0,3,2] row_mask:0xf bank_mask:0xf bound_ctrl:1
	s_nop 1
	v_add_f32_dpp v18, v18, v18 quad_perm:[2,3,0,1] row_mask:0xf bank_mask:0xf bound_ctrl:1
	s_nop 1
	v_add_f32_dpp v18, v18, v18 row_half_mirror row_mask:0xf bank_mask:0xf bound_ctrl:1
	s_nop 1
	v_add_f32_dpp v18, v18, v18 row_mirror row_mask:0xf bank_mask:0xf bound_ctrl:1
	s_nop 1
	v_mov_b32_dpp v43, v18 row_bcast:15 row_mask:0xa bank_mask:0xf
	v_add_f32_e32 v18, v18, v43
	s_nop 1
	v_mov_b32_dpp v58, v18 row_bcast:31 row_mask:0xc bank_mask:0xf
	v_add_f32_e32 v18, v18, v58
	s_nop 0
	v_readlane_b32 s8, v18, 63
	s_nop 1
	v_fma_f32 v18, s8, v42, v41
	v_mul_f32_e32 v38, 0x4b800000, v18
	v_cmp_gt_f32_e32 vcc, s3, v18
	s_nop 1
	v_cndmask_b32_e32 v18, v18, v38, vcc
	v_rsq_f32_e32 v43, v18
	v_lshlrev_b32_e32 v18, 16, v19
	v_and_b32_e32 v19, 0xffff0000, v19
	v_lshl_add_u64 v[38:39], v[6:7], 0, s[10:11]
	v_mul_f32_e32 v48, 0x45800000, v43
	v_cndmask_b32_e32 v48, v43, v48, vcc
	v_pk_mul_f32 v[36:37], v[36:37], v[48:49] op_sel_hi:[1,0]
	v_pk_mul_f32 v[34:35], v[34:35], v[48:49] op_sel_hi:[1,0]
	v_pk_mul_f32 v[32:33], v[32:33], v[48:49] op_sel_hi:[1,0]
	v_pk_mul_f32 v[30:31], v[30:31], v[48:49] op_sel_hi:[1,0]
	v_pk_mul_f32 v[28:29], v[28:29], v[48:49] op_sel_hi:[1,0]
	v_pk_mul_f32 v[26:27], v[26:27], v[48:49] op_sel_hi:[1,0]
	v_pk_mul_f32 v[24:25], v[24:25], v[48:49] op_sel_hi:[1,0]
	v_pk_mul_f32 v[22:23], v[22:23], v[48:49] op_sel_hi:[1,0]
	v_mov_b32_e32 v43, 0
	s_waitcnt vmcnt(0)
	v_pk_fma_f32 v[34:35], v[46:47], v[34:35], v[18:19]
	v_pk_fma_f32 v[36:37], v[44:45], v[36:37], v[20:21]
	v_cvt_pk_bf16_f32 v19, v34, v35
	v_cvt_pk_bf16_f32 v18, v36, v37
	global_store_dwordx2 v[38:39], v[18:19], off
	s_nop 0
	v_mov_b32_e32 v18, v132
	v_mov_b32_e32 v19, v133
	v_mov_b32_e32 v20, v134
	v_mov_b32_e32 v21, v135
	v_lshlrev_b32_e32 v44, 16, v16
	v_and_b32_e32 v45, 0xffff0000, v16
	v_lshlrev_b32_e32 v16, 16, v17
	v_and_b32_e32 v17, 0xffff0000, v17
	s_nop 0
	v_pk_fma_f32 v[20:21], v[20:21], v[30:31], v[16:17]
	v_pk_fma_f32 v[30:31], v[18:19], v[32:33], v[44:45]
	v_cvt_pk_bf16_f32 v17, v20, v21
	v_cvt_pk_bf16_f32 v16, v30, v31
	global_store_dwordx2 v[38:39], v[16:17], off offset:512
	s_nop 0
	v_mov_b32_e32 v16, v136
	v_mov_b32_e32 v17, v137
	v_mov_b32_e32 v18, v138
	v_mov_b32_e32 v19, v139
	v_lshlrev_b32_e32 v32, 16, v14
	v_and_b32_e32 v33, 0xffff0000, v14
	v_lshlrev_b32_e32 v14, 16, v15
	v_and_b32_e32 v15, 0xffff0000, v15
	v_mov_b32_e32 v44, 0
	s_nop 0
	v_pk_fma_f32 v[18:19], v[18:19], v[26:27], v[14:15]
	v_pk_fma_f32 v[26:27], v[16:17], v[28:29], v[32:33]
	v_cvt_pk_bf16_f32 v15, v18, v19
	v_cvt_pk_bf16_f32 v14, v26, v27
	global_store_dwordx2 v[38:39], v[14:15], off offset:1024
	s_nop 0
	v_mov_b32_e32 v14, v140
	v_mov_b32_e32 v15, v141
	v_mov_b32_e32 v16, v142
	v_mov_b32_e32 v17, v143
	v_lshlrev_b32_e32 v28, 16, v12
	v_and_b32_e32 v29, 0xffff0000, v12
	v_lshlrev_b32_e32 v12, 16, v13
	v_and_b32_e32 v13, 0xffff0000, v13
	s_nop 0
	v_pk_fma_f32 v[16:17], v[16:17], v[22:23], v[12:13]
	v_pk_fma_f32 v[22:23], v[14:15], v[24:25], v[28:29]
	v_cvt_pk_bf16_f32 v13, v16, v17
	v_cvt_pk_bf16_f32 v12, v22, v23
	global_store_dwordx2 v[38:39], v[12:13], off offset:1536
	s_nop 0
	v_mov_b32_e32 v12, v144
	v_mov_b32_e32 v13, v145
	v_mov_b32_e32 v14, v146
	v_mov_b32_e32 v15, v147
	v_pk_mul_f32 v[24:25], v[34:35], v[34:35]
	v_pk_mul_f32 v[28:29], v[36:37], v[36:37]
	s_nop 0
	v_pk_mov_b32 v[32:33], v[28:29], v[24:25] op_sel:[1,0]
	v_mov_b32_e32 v29, v25
	v_pk_add_f32 v[24:25], v[32:33], v[28:29]
	v_pk_mul_f32 v[28:29], v[30:31], v[30:31]
	v_pk_mul_f32 v[32:33], v[20:21], v[20:21]
	v_pk_add_f32 v[24:25], v[24:25], v[24:25] op_sel_hi:[0,1]
	v_pk_mov_b32 v[38:39], v[28:29], v[32:33] op_sel:[1,0]
	v_mov_b32_e32 v29, v33
	v_pk_add_f32 v[28:29], v[38:39], v[28:29]
	v_mul_f32_e32 v24, v26, v26
	v_pk_add_f32 v[28:29], v[28:29], v[28:29] op_sel_hi:[0,1]
	v_mul_f32_e32 v28, v18, v18
	v_pk_fma_f32 v[32:33], v[26:27], v[26:27], v[24:25] op_sel_hi:[1,1,0]
	v_pk_fma_f32 v[38:39], v[18:19], v[18:19], v[28:29] op_sel_hi:[1,1,0]
	v_mul_f32_e32 v32, v22, v22
	v_mul_f32_e32 v38, v23, v23
	v_mul_f32_e32 v24, v16, v16
	v_mul_f32_e32 v28, v17, v17
	v_pk_add_f32 v[32:33], v[32:33], v[38:39]
	v_pk_add_f32 v[24:25], v[24:25], v[28:29]
	s_nop 0
	v_pk_add_f32 v[24:25], v[32:33], v[24:25]
	s_nop 0
	v_add_f32_e32 v24, v24, v25
	s_nop 1
	v_add_f32_dpp v24, v24, v24 quad_perm:[1,0,3,2] row_mask:0xf bank_mask:0xf bound_ctrl:1
	s_nop 1
	v_add_f32_dpp v24, v24, v24 quad_perm:[2,3,0,1] row_mask:0xf bank_mask:0xf bound_ctrl:1
	s_nop 1
	v_add_f32_dpp v24, v24, v24 row_half_mirror row_mask:0xf bank_mask:0xf bound_ctrl:1
	s_nop 1
	v_add_f32_dpp v24, v24, v24 row_mirror row_mask:0xf bank_mask:0xf bound_ctrl:1
	s_nop 1
	v_mov_b32_dpp v43, v24 row_bcast:15 row_mask:0xa bank_mask:0xf
	v_add_f32_e32 v24, v24, v43
	s_nop 1
	v_mov_b32_dpp v44, v24 row_bcast:31 row_mask:0xc bank_mask:0xf
	v_add_f32_e32 v24, v24, v44
	s_nop 0
	v_readlane_b32 s8, v24, 63
	s_nop 1
	v_fma_f32 v24, s8, v42, v41
	v_mul_f32_e32 v25, 0x4b800000, v24
	v_cmp_gt_f32_e32 vcc, s3, v24
	s_add_i32 s8, s0, 0x4000
	s_add_u32 s4, s4, s6
	v_cndmask_b32_e32 v24, v24, v25, vcc
	v_rsq_f32_e32 v28, v24
	v_lshl_add_u64 v[24:25], v[4:5], 0, s[10:11]
	s_addc_u32 s5, s5, s7
	s_cmpk_lt_i32 s8, 0x4420
	v_mul_f32_e32 v29, 0x45800000, v28
	v_cndmask_b32_e32 v28, v28, v29, vcc
	v_pk_mul_f32 v[32:33], v[36:37], v[28:29] op_sel_hi:[1,0]
	v_pk_mul_f32 v[34:35], v[34:35], v[28:29] op_sel_hi:[1,0]
	v_pk_mul_f32 v[30:31], v[30:31], v[28:29] op_sel_hi:[1,0]
	v_pk_mul_f32 v[20:21], v[20:21], v[28:29] op_sel_hi:[1,0]
	v_pk_mul_f32 v[18:19], v[18:19], v[28:29] op_sel_hi:[1,0]
	v_pk_mul_f32 v[16:17], v[16:17], v[28:29] op_sel_hi:[1,0]
	s_nop 0
	v_pk_mul_f32 v[14:15], v[14:15], v[34:35]
	v_pk_mul_f32 v[12:13], v[12:13], v[32:33]
	s_nop 0
	v_cvt_pk_bf16_f32 v12, v12, v13
	v_cvt_pk_bf16_f32 v13, v14, v15
	global_store_dwordx2 v[24:25], v[12:13], off
	s_nop 0
	v_mov_b32_e32 v12, v148
	v_mov_b32_e32 v13, v149
	v_mov_b32_e32 v14, v150
	v_mov_b32_e32 v15, v151
	s_nop 0
	v_pk_mul_f32 v[14:15], v[14:15], v[20:21]
	v_pk_mul_f32 v[12:13], v[12:13], v[30:31]
	v_pk_mul_f32 v[20:21], v[26:27], v[28:29] op_sel_hi:[1,0]
	v_cvt_pk_bf16_f32 v12, v12, v13
	v_cvt_pk_bf16_f32 v13, v14, v15
	global_store_dwordx2 v[24:25], v[12:13], off offset:512
	s_nop 0
	v_mov_b32_e32 v12, v152
	v_mov_b32_e32 v13, v153
	v_mov_b32_e32 v14, v154
	v_mov_b32_e32 v15, v155
	s_nop 0
	v_pk_mul_f32 v[14:15], v[14:15], v[18:19]
	v_pk_mul_f32 v[12:13], v[12:13], v[20:21]
	v_pk_mul_f32 v[18:19], v[22:23], v[28:29] op_sel_hi:[1,0]
	v_cvt_pk_bf16_f32 v12, v12, v13
	v_cvt_pk_bf16_f32 v13, v14, v15
	global_store_dwordx2 v[24:25], v[12:13], off offset:1024
	s_nop 0
	v_mov_b32_e32 v12, v156
	v_mov_b32_e32 v13, v157
	v_mov_b32_e32 v14, v158
	v_mov_b32_e32 v15, v159
	s_nop 0
	v_pk_mul_f32 v[14:15], v[14:15], v[16:17]
	v_pk_mul_f32 v[12:13], v[12:13], v[18:19]
	s_nop 0
	v_cvt_pk_bf16_f32 v12, v12, v13
	v_cvt_pk_bf16_f32 v13, v14, v15
	global_store_dwordx2 v[24:25], v[12:13], off offset:1536
	s_cbranch_scc0 .LBB0_2665

.LBB0_2980:
	s_cmp_lt_i32 s88, 19
	s_cselect_b64 s[0:1], -1, 0
	s_cmp_gt_i32 s89, 18
	s_cselect_b64 s[2:3], -1, 0
	s_and_b64 s[0:1], s[0:1], s[2:3]
	s_andn2_b64 vcc, exec, s[0:1]
	s_cbranch_vccnz .LBB0_3034
	v_readlane_b32 s0, v254, 0
	s_waitcnt vmcnt(0)
	v_mbcnt_lo_u32_b32 v0, -1, 0
	s_andn2_b32 s0, s0, 63
	v_mbcnt_hi_u32_b32 v0, -1, v0
	v_or_b32_e32 v66, s0, v0
	v_mov_b32_e32 v0, 0
	s_mov_b32 s3, s90
	v_readlane_b32 s2, v254, 4
	v_readlane_b32 s0, v254, 3
	s_mov_b32 s1, 0
	v_readfirstlane_b32 s0, v66
	s_ashr_i32 s0, s0, 6
	s_mul_i32 s0, s0, s3
	s_add_i32 s0, s2, s0
	s_add_i32 s2, s0, 0x4000
	v_mov_b32_e32 v5, 0
	s_cmpk_gt_i32 s2, 0x441f
	s_waitcnt lgkmcnt(0)
	s_barrier
	s_barrier
	s_cbranch_scc1 .LBB0_2988
	s_load_dwordx4 s[4:7], s[92:93], 0xe0
	s_load_dwordx2 s[10:11], s[92:93], 0xc8
	v_lshlrev_b32_e32 v0, 2, v66
	v_and_b32_e32 v8, 0xfc, v0
	v_lshlrev_b32_e32 v4, 2, v8
	s_waitcnt lgkmcnt(0)
	v_mov_b32_e32 v7, s7
	v_mov_b32_e32 v6, s6
	v_lshl_add_u64 v[0:1], s[10:11], 0, v[4:5]
	s_mov_b64 s[6:7], 0x1000
	v_lshl_add_u64 v[0:1], v[0:1], 0, s[6:7]
	global_load_dwordx4 v[128:131], v[0:1], off
	global_load_dwordx4 v[132:135], v[0:1], off offset:1024
	global_load_dwordx4 v[136:139], v[0:1], off offset:2048
	global_load_dwordx4 v[140:143], v[0:1], off offset:3072
	s_mov_b64 s[6:7], 0x300000
	v_lshlrev_b32_e32 v4, 1, v8
	s_lshl_b32 s8, s3, 3
	v_lshl_add_u64 v[2:3], v[6:7], 0, s[6:7]
	v_lshl_add_u64 v[4:5], v[6:7], 0, v[4:5]
	s_mov_b64 s[6:7], 0x1bc00000
	s_ashr_i32 s3, s2, 31
	v_lshl_add_u64 v[4:5], v[4:5], 0, s[6:7]
	s_lshl_b64 s[6:7], s[2:3], 11
	v_and_b32_e32 v9, 63, v66
	v_lshl_or_b32 v10, v9, 3, s6
	v_mov_b32_e32 v11, s7
	s_ashr_i32 s9, s8, 31
	v_lshl_add_u64 v[6:7], v[6:7], 0, v[10:11]
	s_mov_b64 s[6:7], 0x1f400000
	v_lshl_add_u64 v[6:7], v[6:7], 0, s[6:7]
	s_lshl_b64 s[6:7], s[8:9], 11
	v_mov_b32_e32 v67, 0x358637bd
	s_mov_b32 s10, 0x800000
	v_mov_b32_e32 v68, s5
	v_mov_b32_e32 v69, s4
	v_lshlrev_b32_e32 v70, 2, v8
	v_mov_b32_e32 v71, 0x3a800000
	s_branch .LBB0_2984
.LBB0_2983:
	s_nop 0
	v_mov_b32_e32 v32, v128
	v_mov_b32_e32 v33, v129
	v_mov_b32_e32 v34, v130
	v_mov_b32_e32 v35, v131
	v_pk_mul_f32 v[38:39], v[24:25], v[24:25]
	v_pk_mul_f32 v[40:41], v[28:29], v[28:29]
	v_pk_mul_f32 v[42:43], v[26:27], v[26:27]
	v_pk_mul_f32 v[44:45], v[30:31], v[30:31]
	v_mul_f32_e32 v46, v22, v22
	v_pk_mov_b32 v[50:51], v[44:45], v[42:43] op_sel:[1,0]
	v_mov_b32_e32 v45, v43
	v_pk_mov_b32 v[42:43], v[40:41], v[38:39] op_sel:[1,0]
	v_mov_b32_e32 v41, v39
	v_mul_f32_e32 v48, v20, v20
	v_mov_b32_e32 v49, 0
	v_pk_add_f32 v[44:45], v[50:51], v[44:45]
	v_pk_add_f32 v[40:41], v[42:43], v[40:41]
	v_pk_fma_f32 v[38:39], v[22:23], v[22:23], v[46:47] op_sel_hi:[1,1,0]
	v_pk_fma_f32 v[46:47], v[20:21], v[20:21], v[48:49] op_sel_hi:[1,1,0]
	v_pk_add_f32 v[44:45], v[44:45], v[44:45] op_sel_hi:[0,1]
	v_pk_add_f32 v[40:41], v[40:41], v[40:41] op_sel_hi:[0,1]
	v_mul_f32_e32 v38, v18, v18
	v_mul_f32_e32 v46, v19, v19
	v_mul_f32_e32 v44, v16, v16
	v_mul_f32_e32 v40, v17, v17
	v_pk_add_f32 v[38:39], v[38:39], v[46:47]
	v_pk_add_f32 v[40:41], v[44:45], v[40:41]
	v_mov_b32_e32 v52, 0
	v_pk_add_f32 v[38:39], v[38:39], v[40:41]
	s_add_i32 s4, s0, 0xfffffc00
	v_add_f32_e32 v38, v38, v39
	s_cmpk_lt_i32 s11, 0x4400
	s_cselect_b64 vcc, -1, 0
	v_add_f32_dpp v38, v38, v38 quad_perm:[1,0,3,2] row_mask:0xf bank_mask:0xf bound_ctrl:1
	v_cndmask_b32_e32 v43, v3, v68, vcc
	v_cndmask_b32_e32 v42, v2, v69, vcc
	v_add_f32_dpp v38, v38, v38 quad_perm:[2,3,0,1] row_mask:0xf bank_mask:0xf bound_ctrl:1
	s_cselect_b32 s5, s3, 0
	s_cselect_b32 s4, s2, s4
	v_add_f32_dpp v38, v38, v38 row_half_mirror row_mask:0xf bank_mask:0xf bound_ctrl:1
	s_lshl_b64 s[4:5], s[4:5], 12
	s_waitcnt vmcnt(4)
	v_lshlrev_b32_e32 v36, 16, v14
	v_add_f32_dpp v38, v38, v38 row_mirror row_mask:0xf bank_mask:0xf bound_ctrl:1
	v_and_b32_e32 v37, 0xffff0000, v14
	v_lshlrev_b32_e32 v14, 16, v15
	v_mov_b32_dpp v49, v38 row_bcast:15 row_mask:0xa bank_mask:0xf
	v_add_f32_e32 v38, v38, v49
	v_and_b32_e32 v15, 0xffff0000, v15
	s_add_i32 s0, s0, s8
	v_mov_b32_dpp v52, v38 row_bcast:31 row_mask:0xc bank_mask:0xf
	v_add_f32_e32 v38, v38, v52
	v_lshl_add_u64 v[6:7], v[6:7], 0, s[6:7]
	v_readlane_b32 s11, v38, 63
	s_nop 1
	v_fma_f32 v38, s11, v71, v67
	v_mul_f32_e32 v39, 0x4b800000, v38
	v_cmp_gt_f32_e32 vcc, s10, v38
	s_add_i32 s11, s0, 0x4000
	s_add_u32 s2, s2, s8
	v_cndmask_b32_e32 v38, v38, v39, vcc
	v_rsq_f32_e32 v40, v38
	v_lshl_add_u64 v[38:39], v[42:43], 0, s[4:5]
	s_addc_u32 s3, s3, s9
	v_readfirstlane_b32 s4, v38
	v_mul_f32_e32 v38, 0x45800000, v40
	v_cndmask_b32_e32 v38, v40, v38, vcc
	v_pk_mul_f32 v[30:31], v[30:31], v[38:39] op_sel_hi:[1,0]
	v_pk_mul_f32 v[26:27], v[26:27], v[38:39] op_sel_hi:[1,0]
	v_readfirstlane_b32 s5, v39
	v_pk_mul_f32 v[24:25], v[24:25], v[38:39] op_sel_hi:[1,0]
	v_pk_mul_f32 v[20:21], v[20:21], v[38:39] op_sel_hi:[1,0]
	v_pk_mul_f32 v[16:17], v[16:17], v[38:39] op_sel_hi:[1,0]
	s_cmpk_lt_i32 s11, 0x4420
	s_waitcnt vmcnt(0)
	v_pk_fma_f32 v[34:35], v[34:35], v[26:27], v[14:15]
	v_pk_fma_f32 v[32:33], v[32:33], v[30:31], v[36:37]
	global_store_dwordx4 v70, v[32:35], s[4:5]
	s_nop 0
	v_mov_b32_e32 v30, v132
	v_mov_b32_e32 v31, v133
	v_mov_b32_e32 v32, v134
	v_mov_b32_e32 v33, v135
	v_lshlrev_b32_e32 v14, 16, v12
	v_and_b32_e32 v15, 0xffff0000, v12
	v_lshlrev_b32_e32 v26, 16, v13
	v_and_b32_e32 v27, 0xffff0000, v13
	v_pk_mul_f32 v[12:13], v[28:29], v[38:39] op_sel_hi:[1,0]
	s_nop 0
	v_pk_fma_f32 v[12:13], v[30:31], v[12:13], v[14:15]
	v_pk_fma_f32 v[14:15], v[32:33], v[24:25], v[26:27]
	global_store_dwordx4 v70, v[12:15], s[4:5] offset:1024
	s_nop 0
	v_mov_b32_e32 v12, v136
	v_mov_b32_e32 v13, v137
	v_mov_b32_e32 v14, v138
	v_mov_b32_e32 v15, v139
	v_lshlrev_b32_e32 v24, 16, v10
	v_and_b32_e32 v25, 0xffff0000, v10
	v_lshlrev_b32_e32 v26, 16, v11
	v_and_b32_e32 v27, 0xffff0000, v11
	v_pk_mul_f32 v[10:11], v[22:23], v[38:39] op_sel_hi:[1,0]
	s_nop 0
	v_pk_fma_f32 v[10:11], v[12:13], v[10:11], v[24:25]
	v_pk_fma_f32 v[12:13], v[14:15], v[20:21], v[26:27]
	global_store_dwordx4 v70, v[10:13], s[4:5] offset:2048
	s_nop 0
	v_mov_b32_e32 v10, v140
	v_mov_b32_e32 v11, v141
	v_mov_b32_e32 v12, v142
	v_mov_b32_e32 v13, v143
	v_lshlrev_b32_e32 v14, 16, v8
	v_and_b32_e32 v15, 0xffff0000, v8
	v_lshlrev_b32_e32 v20, 16, v9
	v_and_b32_e32 v21, 0xffff0000, v9
	v_pk_mul_f32 v[8:9], v[18:19], v[38:39] op_sel_hi:[1,0]
	s_nop 0
	v_pk_fma_f32 v[8:9], v[10:11], v[8:9], v[14:15]
	v_pk_fma_f32 v[10:11], v[12:13], v[16:17], v[20:21]
	global_store_dwordx4 v70, v[8:11], s[4:5] offset:3072
	s_cbranch_scc0 .LBB0_2988
